# attention bias-table fill: 9 loads issued together (last lane-0 only) with counted vmcnt waits instead of 9 dependent round trips
# speedup vs baseline: 1.0189x; 1.0023x over previous
.LBB0_940:
	v_mbcnt_lo_u32_b32 v5, -1, 0
	v_mbcnt_hi_u32_b32 v5, -1, v5
	global_load_dword v6, v[2:3], off
	global_load_dword v7, v[2:3], off offset:256
	global_load_dword v8, v[2:3], off offset:512
	global_load_dword v9, v[2:3], off offset:768
	global_load_dword v10, v[2:3], off offset:1024
	global_load_dword v11, v[2:3], off offset:1280
	global_load_dword v12, v[2:3], off offset:1536
	global_load_dword v13, v[2:3], off offset:1792
	v_cmp_eq_u32_e32 vcc, 0, v5
	s_and_saveexec_b64 s[18:19], vcc
	global_load_dword v14, v[2:3], off offset:2048
	s_mov_b64 exec, s[18:19]
	s_waitcnt vmcnt(8)
	v_mul_f32_e32 v6, 0x3fb8aa3b, v6
	ds_write_b32 v209, v6
	s_waitcnt vmcnt(7)
	v_mul_f32_e32 v7, 0x3fb8aa3b, v7
	ds_write_b32 v209, v7 offset:256
	s_waitcnt vmcnt(6)
	v_mul_f32_e32 v8, 0x3fb8aa3b, v8
	ds_write_b32 v209, v8 offset:512
	s_waitcnt vmcnt(5)
	v_mul_f32_e32 v9, 0x3fb8aa3b, v9
	ds_write_b32 v209, v9 offset:768
	s_waitcnt vmcnt(4)
	v_mul_f32_e32 v10, 0x3fb8aa3b, v10
	ds_write_b32 v209, v10 offset:1024
	s_waitcnt vmcnt(3)
	v_mul_f32_e32 v11, 0x3fb8aa3b, v11
	ds_write_b32 v209, v11 offset:1280
	s_waitcnt vmcnt(2)
	v_mul_f32_e32 v12, 0x3fb8aa3b, v12
	ds_write_b32 v209, v12 offset:1536
	s_waitcnt vmcnt(1)
	v_mul_f32_e32 v13, 0x3fb8aa3b, v13
	ds_write_b32 v209, v13 offset:1792
	s_and_saveexec_b64 s[18:19], vcc
	s_waitcnt vmcnt(0)
	v_mul_f32_e32 v14, 0x3fb8aa3b, v14
	ds_write_b32 v209, v14 offset:2048
	s_mov_b64 exec, s[18:19]
	s_or_b64 exec, exec, s[18:19]
	v_mov_b32_e32 v215, v4
